# scan trims (no stepper nop, producer reads prefetch regs), xcd barrier instead of cg grid sync, interleaved packed chains
# speedup vs baseline: 1.0257x; 1.0098x over previous
; __device__ __forceinline__ int tid_opaque() { int t; asm volatile("v_mov_b32 %0, %1" : "=v"(t) : "v"((int)threadIdx.x)); __builtin_assume(t >= 0 && t < NTHREADS); return t; }
; __global__ void __launch_bounds__(NTHREADS, 2) mega(Args a_unused) {
;     ...
;     for (int p = plo; p < phi; ++p) {
;         unsigned char* ws = a.ws();
;         if (p == plo + 1) grid.sync();
;         else if (p > plo) xcd_barrier(xbar);
;         const int tid = tid_opaque(), lane = tid & 63, wave = __builtin_amdgcn_readfirstlane(tid >> 6);
.LBB0_10:
	s_waitcnt vmcnt(0)
	ds_read_b64 v[2:3], v193
	v_readlane_b32 s0, v253, 6
	v_writelane_b32 v255, s1, 12
	s_cmp_lg_u32 s1, s0
	s_mov_b64 s[2:3], 0
	s_waitcnt lgkmcnt(0)
	v_readfirstlane_b32 s1, v3
	v_readfirstlane_b32 s0, v2
	s_nop 1
	v_writelane_b32 v255, s0, 13
	s_nop 1
	v_writelane_b32 v255, s1, 14
	s_mov_b64 s[0:1], -1
	s_nop 0
	v_readlane_b32 s2, v253, 4
	v_readlane_b32 s3, v255, 12
	s_mov_b64 s[0:1], 0
	s_cmp_gt_i32 s3, s2
	s_mov_b64 s[2:3], 0
	s_cbranch_scc0 .LBB0_57
	s_waitcnt vmcnt(0)
	s_barrier
	s_mov_b64 s[2:3], exec
	v_readlane_b32 s4, v253, 2
	v_readlane_b32 s5, v253, 3
	s_and_b64 s[4:5], s[2:3], s[4:5]
	s_mov_b64 exec, s[4:5]
	s_cbranch_execz .LBB0_56
	v_readlane_b32 s4, v254, 20
	s_waitcnt vmcnt(0) expcnt(0) lgkmcnt(0)
	s_nop 0
	v_mov_b32_e32 v0, s4
	ds_read_b32 v2, v0
	v_readlane_b32 s4, v254, 21
	s_waitcnt lgkmcnt(0)
	v_cmp_ne_u32_e32 vcc, 0, v2
	v_mov_b32_e32 v0, s4
	ds_read_b32 v0, v0
	s_cbranch_vccnz .LBB0_27
	s_mov_b32 s12, 1
	s_mov_b64 s[4:5], 0
	s_branch .LBB0_17

; #define LAS __attribute__((address_space(3)))
; #define MFMA32(a, b, c) __builtin_amdgcn_mfma_f32_32x32x16_bf16((a), (b), (c), 0, 0, 0)
; __device__ __forceinline__ float fexp2(float x) { return __builtin_amdgcn_exp2f(x); }
; __device__ __forceinline__ void diff_unit(LAS unsigned char* lds, const AP a, int l, int grp, int bl, int hd, int qb) {
;     ...
;             float ls = 0.f;
; #pragma unroll
;             for (int r = 0; r < 16; ++r) { st0[r] = fexp2(st0[r]); st1[r] = fexp2(st1[r]); ls += st0[r] + st1[r]; }
;             lsum += ls;
;             const bf16x8 p0 = pack8(st0, 0), p1 = pack8(st0, 1), p2 = pack8(st1, 0), p3 = pack8(st1, 1);
; #pragma unroll
;             for (int dvb = 0; dvb < 4; ++dvb) {
;                 const bf16x8 v0 = *(const LAS bf16x8*)(bb + vrd + (dvb * 32 * VSTR) * 2);
;                 const bf16x8 v1 = *(const LAS bf16x8*)(bb + vrd + (dvb * 32 * VSTR + 16) * 2);
;                 o[dvb] = MFMA32(v0, p0, o[dvb]); o[dvb] = MFMA32(v1, p1, o[dvb]);
;                 if (a1c) {
;                     const bf16x8 v2 = *(const LAS bf16x8*)(bb + vrd + (dvb * 32 * VSTR + 32) * 2);
;                     const bf16x8 v3 = *(const LAS bf16x8*)(bb + vrd + (dvb * 32 * VSTR + 48) * 2);
;                     o[dvb] = MFMA32(v2, p2, o[dvb]); o[dvb] = MFMA32(v3, p3, o[dvb]); }
;             }
.Ldf_f_nsh:
	s_waitcnt lgkmcnt(7)
	v_sub_u32_e32 v2, v224, v2
	s_movk_i32 s7, 0x7f
	v_cmp_lt_i32_e32 vcc, s7, v2
	s_mov_b64 s[20:21], exec
	s_nop 0
	v_cndmask_b32_e32 v2, 0, v225, vcc
	s_mov_b64 s[16:17], vcc
	v_sub_f32_e32 v82, v2, v14
	v_mov_b32_e32 v83, v82
	v_mov_b64_e32 v[84:85], v[82:83]
	v_mov_b64_e32 v[86:87], v[82:83]
	v_mov_b64_e32 v[88:89], v[82:83]
	v_mov_b64_e32 v[90:91], v[82:83]
	v_mov_b64_e32 v[92:93], v[82:83]
	v_mov_b64_e32 v[94:95], v[82:83]
	v_mov_b64_e32 v[96:97], v[82:83]
	v_mov_b64_e32 v[98:99], v[82:83]
	v_mov_b64_e32 v[100:101], v[82:83]
	v_mov_b64_e32 v[102:103], v[82:83]
	v_mov_b64_e32 v[104:105], v[82:83]
	v_mov_b64_e32 v[106:107], v[82:83]
	v_mov_b64_e32 v[108:109], v[82:83]
	v_mov_b64_e32 v[110:111], v[82:83]
	v_mov_b64_e32 v[112:113], v[82:83]
	s_waitcnt lgkmcnt(6)
	v_mfma_f32_32x32x16_bf16 v[82:97], v[6:9], v[146:149], v[82:97]
	ds_read_b128 v[6:9], v252 offset:8800
	s_mul_i32 s0, s14, 0x8c00
	v_exp_f32_e32 v114, v114
	v_exp_f32_e32 v115, v115
	v_exp_f32_e32 v116, v116
	s_waitcnt lgkmcnt(6)
	v_mfma_f32_32x32x16_bf16 v[98:113], v[200:203], v[146:149], v[98:113]
	v_add_u32_e32 v252, s0, v228
	ds_read_b128 v[200:203], v252 offset:17408
	v_exp_f32_e32 v117, v117
	v_exp_f32_e32 v118, v118
	v_exp_f32_e32 v119, v119
	s_waitcnt lgkmcnt(6)
	v_mfma_f32_32x32x16_bf16 v[82:97], v[10:13], v[150:153], v[82:97]
	v_exp_f32_e32 v120, v120
	v_exp_f32_e32 v121, v121
	v_cvt_pk_bf16_f32 v2, v114, v115
	s_waitcnt lgkmcnt(5)
	v_mfma_f32_32x32x16_bf16 v[98:113], v[242:245], v[150:153], v[98:113]
	ds_read_b128 v[242:245], v252 offset:22016
	v_cvt_pk_bf16_f32 v3, v116, v117
	v_cvt_pk_bf16_f32 v4, v118, v119
	v_cvt_pk_bf16_f32 v5, v120, v121
	s_waitcnt lgkmcnt(5)
	v_mfma_f32_32x32x16_bf16 v[82:97], v[234:237], v[154:157], v[82:97]
	ds_read_b128 v[234:237], v252 offset:26624
	v_pk_add_f32 v[250:251], v[114:115], v[116:117]
	v_exp_f32_e32 v122, v122
	v_exp_f32_e32 v123, v123
	s_waitcnt lgkmcnt(5)
	v_mfma_f32_32x32x16_bf16 v[98:113], v[246:249], v[154:157], v[98:113]
	ds_read_b128 v[246:249], v252 offset:31232
	v_pk_add_f32 v[250:251], v[250:251], v[118:119]
	v_exp_f32_e32 v124, v124
	v_exp_f32_e32 v125, v125
	s_waitcnt lgkmcnt(5)
	v_mfma_f32_32x32x16_bf16 v[82:97], v[238:241], v[158:161], v[82:97]
	v_pk_add_f32 v[250:251], v[250:251], v[120:121]
	v_exp_f32_e32 v126, v126
	v_exp_f32_e32 v127, v127
	s_waitcnt lgkmcnt(4)
	v_mfma_f32_32x32x16_bf16 v[98:113], v[6:9], v[158:161], v[98:113]
	v_exp_f32_e32 v128, v128
	v_exp_f32_e32 v129, v129
	s_waitcnt lgkmcnt(3)
	v_mfma_f32_32x32x16_bf16 v[48:63], v[200:203], v[2:5], v[48:63]
	ds_read_b128 v[200:203], v252 offset:17440
	v_cvt_pk_bf16_f32 v114, v122, v123
	v_cvt_pk_bf16_f32 v115, v124, v125
	s_waitcnt lgkmcnt(3)
	v_mfma_f32_32x32x16_bf16 v[32:47], v[242:245], v[2:5], v[32:47]
	ds_read_b128 v[242:245], v252 offset:22048
	v_cvt_pk_bf16_f32 v116, v126, v127
	v_cvt_pk_bf16_f32 v117, v128, v129
	s_waitcnt lgkmcnt(3)
	v_mfma_f32_32x32x16_bf16 v[16:31], v[234:237], v[2:5], v[16:31]
	ds_read_b128 v[234:237], v252 offset:26656
	v_exp_f32_e32 v130, v130
	v_exp_f32_e32 v131, v131
	v_exp_f32_e32 v132, v132
	s_waitcnt lgkmcnt(3)
	v_mfma_f32_32x32x16_bf16 v[64:79], v[246:249], v[2:5], v[64:79]
	ds_read_b128 v[246:249], v252 offset:31264
	v_exp_f32_e32 v133, v133
	v_exp_f32_e32 v134, v134
	v_pk_add_f32 v[250:251], v[250:251], v[122:123]
	s_waitcnt lgkmcnt(3)
	v_mfma_f32_32x32x16_bf16 v[48:63], v[200:203], v[114:117], v[48:63]
	ds_read_b128 v[200:203], v252 offset:17472
	v_exp_f32_e32 v135, v135
	v_exp_f32_e32 v136, v136
	v_exp_f32_e32 v137, v137
	s_waitcnt lgkmcnt(3)
	v_mfma_f32_32x32x16_bf16 v[32:47], v[242:245], v[114:117], v[32:47]
	ds_read_b128 v[242:245], v252 offset:22080
	v_exp_f32_e32 v138, v138
	v_exp_f32_e32 v139, v139
	v_pk_add_f32 v[250:251], v[250:251], v[124:125]
	s_waitcnt lgkmcnt(3)
	v_mfma_f32_32x32x16_bf16 v[16:31], v[234:237], v[114:117], v[16:31]
	ds_read_b128 v[234:237], v252 offset:26688
	v_exp_f32_e32 v140, v140
	v_exp_f32_e32 v141, v141
	v_pk_add_f32 v[250:251], v[250:251], v[126:127]
	s_waitcnt lgkmcnt(3)
	v_mfma_f32_32x32x16_bf16 v[64:79], v[246:249], v[114:117], v[64:79]
	ds_read_b128 v[246:249], v252 offset:31296
	v_cvt_pk_bf16_f32 v10, v130, v131
	v_cvt_pk_bf16_f32 v11, v132, v133
	v_cvt_pk_bf16_f32 v12, v134, v135
	v_cvt_pk_bf16_f32 v13, v136, v137
	v_exp_f32_e32 v142, v142
	v_exp_f32_e32 v143, v143
	s_waitcnt lgkmcnt(3)
	v_mfma_f32_32x32x16_bf16 v[48:63], v[200:203], v[10:13], v[48:63]
	ds_read_b128 v[200:203], v252 offset:17504
	v_exp_f32_e32 v144, v144
	v_exp_f32_e32 v145, v145
	v_pk_add_f32 v[250:251], v[250:251], v[128:129]
	s_waitcnt lgkmcnt(3)
	v_mfma_f32_32x32x16_bf16 v[32:47], v[242:245], v[10:13], v[32:47]
	ds_read_b128 v[242:245], v252 offset:22112
	v_cvt_pk_bf16_f32 v6, v138, v139
	v_cvt_pk_bf16_f32 v7, v140, v141
	v_cvt_pk_bf16_f32 v8, v142, v143
	s_waitcnt lgkmcnt(3)
	v_mfma_f32_32x32x16_bf16 v[16:31], v[234:237], v[10:13], v[16:31]
	ds_read_b128 v[234:237], v252 offset:26720
	v_cvt_pk_bf16_f32 v9, v144, v145
	v_pk_add_f32 v[238:239], v[130:131], v[132:133]
	s_waitcnt lgkmcnt(3)
	v_mfma_f32_32x32x16_bf16 v[64:79], v[246:249], v[10:13], v[64:79]
	ds_read_b128 v[246:249], v252 offset:31328
	v_pk_add_f32 v[250:251], v[250:251], v[134:135]
	v_pk_add_f32 v[238:239], v[238:239], v[136:137]
	v_pk_add_f32 v[250:251], v[250:251], v[138:139]
	s_waitcnt lgkmcnt(3)
	v_mfma_f32_32x32x16_bf16 v[48:63], v[200:203], v[6:9], v[48:63]
	v_pk_add_f32 v[238:239], v[238:239], v[140:141]
	v_pk_add_f32 v[250:251], v[250:251], v[142:143]
	v_pk_add_f32 v[238:239], v[238:239], v[144:145]
	s_waitcnt lgkmcnt(2)
	v_mfma_f32_32x32x16_bf16 v[32:47], v[242:245], v[6:9], v[32:47]
	v_pk_add_f32 v[250:251], v[250:251], v[238:239]
	s_waitcnt lgkmcnt(1)
	v_mfma_f32_32x32x16_bf16 v[16:31], v[234:237], v[6:9], v[16:31]
	v_add_f32_e32 v250, v250, v251
	s_waitcnt lgkmcnt(0)
	v_mfma_f32_32x32x16_bf16 v[64:79], v[246:249], v[6:9], v[64:79]
	v_add_f32_e32 v80, v80, v250
	s_branch .LBB0_177

; #define LAS __attribute__((address_space(3)))
; __device__ __forceinline__ void scan_job(LAS unsigned char* lds, const AP a, int l, int bl, int hd, int rh) {
;     ...
;             for (int st = 0; st < CH; ++st) {
;                 const f32x4 w = wN, kk = kkN, b = bN, k = kN, r = rN; const f32x2 v = vN;
;                 const int on = ((st + 1) & (CH - 1)) * 64;
;                 rN = *(const LAS f32x4*)(bp + on + o0); wN = *(const LAS f32x4*)(bp + VSZ + on + o0); kN = *(const LAS f32x4*)(bp + 2 * VSZ + on + o0); kkN = *(const LAS f32x4*)(bp + 4 * VSZ + on + o0); bN = *(const LAS f32x4*)(bp + 5 * VSZ + on + o0);
;                 vN = *(const LAS f32x2*)(bp + on + vo);
;                 const f32x2 kk0 = {kk.x, kk.y}, kk1 = {kk.z, kk.w}, w0 = {w.x, w.y}, w1 = {w.z, w.w}, b0 = {b.x, b.y}, b1 = {b.z, b.w}, k0 = {k.x, k.y}, k1 = {k.z, k.w}, r0 = {r.x, r.y}, r1 = {r.z, r.w};
;                 const f32x2 va = {v.x, v.x}, vb = {v.y, v.y};
;                 const f32x2 pa = sA0 * kk0 + sA1 * kk1, pb = sB0 * kk0 + sB1 * kk1;
;                 const float saA = -red16(pa.x + pa.y), saB = -red16(pb.x + pb.y);
;                 const f32x2 sav = {saA, saA}, sbv = {saB, saB};
;                 sA0 = sA0 * w0 + (sav * b0 + va * k0); sA1 = sA1 * w1 + (sav * b1 + va * k1);
;                 sB0 = sB0 * w0 + (sbv * b0 + vb * k0); sB1 = sB1 * w1 + (sbv * b1 + vb * k1);
;                 const f32x2 ya = sA0 * r0 + sA1 * r1, yb = sB0 * r0 + sB1 * r1;
;                 *(LAS f32x2*)(yl + st * 16 * YSTR) = (f32x2){ya.x + ya.y, yb.x + yb.y};
.LBB0_252:
	s_waitcnt lgkmcnt(1)
	ds_read_b128 v[46:49], v0
	ds_read_b128 v[50:53], v0 offset:4096
	ds_read_b128 v[54:57], v0 offset:8192
	ds_read_b128 v[62:65], v0 offset:16384
	ds_read_b128 v[58:61], v0 offset:20480
	ds_read_b64 v[84:85], v95
	v_pk_mul_f32 v[112:113], v[74:75], v[42:43] op_sel_hi:[1,0]
	v_pk_mul_f32 v[104:105], v[82:83], v[34:35] op_sel_hi:[1,0]
	v_pk_fma_f32 v[112:113], v[76:77], v[42:43], v[112:113] op_sel:[0,1,0]
	v_pk_mul_f32 v[106:107], v[82:83], v[34:35] op_sel:[0,1]
	v_pk_fma_f32 v[112:113], v[78:79], v[44:45], v[112:113] op_sel_hi:[1,0,1]
	v_pk_mul_f32 v[108:109], v[82:83], v[36:37] op_sel_hi:[1,0]
	v_pk_fma_f32 v[112:113], v[80:81], v[44:45], v[112:113] op_sel:[0,1,0]
	v_pk_mul_f32 v[110:111], v[82:83], v[36:37] op_sel:[0,1]
	v_pk_fma_f32 v[104:105], v[74:75], v[30:31], v[104:105] op_sel_hi:[1,0,1]
	v_add_f32_dpp v112, v112, v112 quad_perm:[1,0,3,2] row_mask:0xf bank_mask:0xf bound_ctrl:1
	v_add_f32_dpp v113, v113, v113 quad_perm:[1,0,3,2] row_mask:0xf bank_mask:0xf bound_ctrl:1
	v_pk_fma_f32 v[106:107], v[76:77], v[30:31], v[106:107] op_sel:[0,1,0]
	v_add_f32_dpp v112, v112, v112 quad_perm:[2,3,0,1] row_mask:0xf bank_mask:0xf bound_ctrl:1
	v_add_f32_dpp v113, v113, v113 quad_perm:[2,3,0,1] row_mask:0xf bank_mask:0xf bound_ctrl:1
	v_pk_fma_f32 v[108:109], v[78:79], v[32:33], v[108:109] op_sel_hi:[1,0,1]
	v_add_f32_dpp v112, v112, v112 row_half_mirror row_mask:0xf bank_mask:0xf bound_ctrl:1
	v_add_f32_dpp v113, v113, v113 row_half_mirror row_mask:0xf bank_mask:0xf bound_ctrl:1
	v_pk_fma_f32 v[110:111], v[80:81], v[32:33], v[110:111] op_sel:[0,1,0]
	v_add_f32_dpp v112, v112, v112 row_mirror row_mask:0xf bank_mask:0xf bound_ctrl:1
	v_add_f32_dpp v113, v113, v113 row_mirror row_mask:0xf bank_mask:0xf bound_ctrl:1
	v_pk_fma_f32 v[74:75], v[112:113], v[38:39], v[104:105] op_sel_hi:[1,0,1] neg_lo:[1,0,0] neg_hi:[1,0,0]
	v_pk_fma_f32 v[76:77], v[112:113], v[38:39], v[106:107] op_sel:[0,1,0] neg_lo:[1,0,0] neg_hi:[1,0,0]
	v_pk_mul_f32 v[114:115], v[74:75], v[26:27] op_sel_hi:[1,0]
	v_pk_fma_f32 v[78:79], v[112:113], v[40:41], v[108:109] op_sel_hi:[1,0,1] neg_lo:[1,0,0] neg_hi:[1,0,0]
	v_pk_fma_f32 v[114:115], v[76:77], v[26:27], v[114:115] op_sel:[0,1,0]
	v_pk_fma_f32 v[80:81], v[112:113], v[40:41], v[110:111] op_sel:[0,1,0] neg_lo:[1,0,0] neg_hi:[1,0,0]
	v_pk_fma_f32 v[114:115], v[78:79], v[28:29], v[114:115] op_sel_hi:[1,0,1]
	v_pk_fma_f32 v[114:115], v[80:81], v[28:29], v[114:115] op_sel:[0,1,0]
	ds_write_b64 v96, v[114:115]
	s_waitcnt lgkmcnt(1)
	ds_read_b128 v[26:29], v0 offset:256
	ds_read_b128 v[30:33], v0 offset:4352
	ds_read_b128 v[34:37], v0 offset:8448
	ds_read_b128 v[42:45], v0 offset:16640
	ds_read_b128 v[38:41], v0 offset:20736
	ds_read_b64 v[82:83], v95 offset:256
	v_pk_mul_f32 v[112:113], v[74:75], v[62:63] op_sel_hi:[1,0]
	v_pk_mul_f32 v[104:105], v[84:85], v[54:55] op_sel_hi:[1,0]
	v_pk_fma_f32 v[112:113], v[76:77], v[62:63], v[112:113] op_sel:[0,1,0]
	v_pk_mul_f32 v[106:107], v[84:85], v[54:55] op_sel:[0,1]
	v_pk_fma_f32 v[112:113], v[78:79], v[64:65], v[112:113] op_sel_hi:[1,0,1]
	v_pk_mul_f32 v[108:109], v[84:85], v[56:57] op_sel_hi:[1,0]
	v_pk_fma_f32 v[112:113], v[80:81], v[64:65], v[112:113] op_sel:[0,1,0]
	v_pk_mul_f32 v[110:111], v[84:85], v[56:57] op_sel:[0,1]
	v_pk_fma_f32 v[104:105], v[74:75], v[50:51], v[104:105] op_sel_hi:[1,0,1]
	v_add_f32_dpp v112, v112, v112 quad_perm:[1,0,3,2] row_mask:0xf bank_mask:0xf bound_ctrl:1
	v_add_f32_dpp v113, v113, v113 quad_perm:[1,0,3,2] row_mask:0xf bank_mask:0xf bound_ctrl:1
	v_pk_fma_f32 v[106:107], v[76:77], v[50:51], v[106:107] op_sel:[0,1,0]
	v_add_f32_dpp v112, v112, v112 quad_perm:[2,3,0,1] row_mask:0xf bank_mask:0xf bound_ctrl:1
	v_add_f32_dpp v113, v113, v113 quad_perm:[2,3,0,1] row_mask:0xf bank_mask:0xf bound_ctrl:1
	v_pk_fma_f32 v[108:109], v[78:79], v[52:53], v[108:109] op_sel_hi:[1,0,1]
	v_add_f32_dpp v112, v112, v112 row_half_mirror row_mask:0xf bank_mask:0xf bound_ctrl:1
	v_add_f32_dpp v113, v113, v113 row_half_mirror row_mask:0xf bank_mask:0xf bound_ctrl:1
	v_pk_fma_f32 v[110:111], v[80:81], v[52:53], v[110:111] op_sel:[0,1,0]
	v_add_f32_dpp v112, v112, v112 row_mirror row_mask:0xf bank_mask:0xf bound_ctrl:1
	v_add_f32_dpp v113, v113, v113 row_mirror row_mask:0xf bank_mask:0xf bound_ctrl:1
	v_pk_fma_f32 v[74:75], v[112:113], v[58:59], v[104:105] op_sel_hi:[1,0,1] neg_lo:[1,0,0] neg_hi:[1,0,0]
	v_pk_fma_f32 v[76:77], v[112:113], v[58:59], v[106:107] op_sel:[0,1,0] neg_lo:[1,0,0] neg_hi:[1,0,0]
	v_pk_mul_f32 v[114:115], v[74:75], v[46:47] op_sel_hi:[1,0]
	v_pk_fma_f32 v[78:79], v[112:113], v[60:61], v[108:109] op_sel_hi:[1,0,1] neg_lo:[1,0,0] neg_hi:[1,0,0]
	v_pk_fma_f32 v[114:115], v[76:77], v[46:47], v[114:115] op_sel:[0,1,0]
	v_pk_fma_f32 v[80:81], v[112:113], v[60:61], v[110:111] op_sel:[0,1,0] neg_lo:[1,0,0] neg_hi:[1,0,0]
	v_pk_fma_f32 v[114:115], v[78:79], v[48:49], v[114:115] op_sel_hi:[1,0,1]
	v_pk_fma_f32 v[114:115], v[80:81], v[48:49], v[114:115] op_sel:[0,1,0]
	ds_write_b64 v96, v[114:115] offset:2176
	s_waitcnt lgkmcnt(1)
; #define LAS __attribute__((address_space(3)))
; __device__ __forceinline__ void scan_job(LAS unsigned char* lds, const AP a, int l, int bl, int hd, int rh) {
;     ...
;             for (int st = 0; st < CH; ++st) {
;                 const f32x4 w = wN, kk = kkN, b = bN, k = kN, r = rN; const f32x2 v = vN;
;                 const int on = ((st + 1) & (CH - 1)) * 64;
;                 rN = *(const LAS f32x4*)(bp + on + o0); wN = *(const LAS f32x4*)(bp + VSZ + on + o0); kN = *(const LAS f32x4*)(bp + 2 * VSZ + on + o0); kkN = *(const LAS f32x4*)(bp + 4 * VSZ + on + o0); bN = *(const LAS f32x4*)(bp + 5 * VSZ + on + o0);
;                 vN = *(const LAS f32x2*)(bp + on + vo);
;                 const f32x2 kk0 = {kk.x, kk.y}, kk1 = {kk.z, kk.w}, w0 = {w.x, w.y}, w1 = {w.z, w.w}, b0 = {b.x, b.y}, b1 = {b.z, b.w}, k0 = {k.x, k.y}, k1 = {k.z, k.w}, r0 = {r.x, r.y}, r1 = {r.z, r.w};
;                 const f32x2 va = {v.x, v.x}, vb = {v.y, v.y};
;                 const f32x2 pa = sA0 * kk0 + sA1 * kk1, pb = sB0 * kk0 + sB1 * kk1;
;                 const float saA = -red16(pa.x + pa.y), saB = -red16(pb.x + pb.y);
;                 const f32x2 sav = {saA, saA}, sbv = {saB, saB};
;                 sA0 = sA0 * w0 + (sav * b0 + va * k0); sA1 = sA1 * w1 + (sav * b1 + va * k1);
;                 sB0 = sB0 * w0 + (sbv * b0 + vb * k0); sB1 = sB1 * w1 + (sbv * b1 + vb * k1);
;                 const f32x2 ya = sA0 * r0 + sA1 * r1, yb = sB0 * r0 + sB1 * r1;
;                 *(LAS f32x2*)(yl + st * 16 * YSTR) = (f32x2){ya.x + ya.y, yb.x + yb.y};
;             }
	ds_read_b128 v[46:49], v0 offset:512
	ds_read_b128 v[50:53], v0 offset:4608
	ds_read_b128 v[54:57], v0 offset:8704
	ds_read_b128 v[62:65], v0 offset:16896
	ds_read_b128 v[58:61], v0 offset:20992
	ds_read_b64 v[84:85], v95 offset:512
	v_pk_mul_f32 v[112:113], v[74:75], v[42:43] op_sel_hi:[1,0]
	v_pk_mul_f32 v[104:105], v[82:83], v[34:35] op_sel_hi:[1,0]
	v_pk_fma_f32 v[112:113], v[76:77], v[42:43], v[112:113] op_sel:[0,1,0]
	v_pk_mul_f32 v[106:107], v[82:83], v[34:35] op_sel:[0,1]
	v_pk_fma_f32 v[112:113], v[78:79], v[44:45], v[112:113] op_sel_hi:[1,0,1]
	v_pk_mul_f32 v[108:109], v[82:83], v[36:37] op_sel_hi:[1,0]
	v_pk_fma_f32 v[112:113], v[80:81], v[44:45], v[112:113] op_sel:[0,1,0]
	v_pk_mul_f32 v[110:111], v[82:83], v[36:37] op_sel:[0,1]
	v_pk_fma_f32 v[104:105], v[74:75], v[30:31], v[104:105] op_sel_hi:[1,0,1]
	v_add_f32_dpp v112, v112, v112 quad_perm:[1,0,3,2] row_mask:0xf bank_mask:0xf bound_ctrl:1
	v_add_f32_dpp v113, v113, v113 quad_perm:[1,0,3,2] row_mask:0xf bank_mask:0xf bound_ctrl:1
	v_pk_fma_f32 v[106:107], v[76:77], v[30:31], v[106:107] op_sel:[0,1,0]
	v_add_f32_dpp v112, v112, v112 quad_perm:[2,3,0,1] row_mask:0xf bank_mask:0xf bound_ctrl:1
	v_add_f32_dpp v113, v113, v113 quad_perm:[2,3,0,1] row_mask:0xf bank_mask:0xf bound_ctrl:1
	v_pk_fma_f32 v[108:109], v[78:79], v[32:33], v[108:109] op_sel_hi:[1,0,1]
	v_add_f32_dpp v112, v112, v112 row_half_mirror row_mask:0xf bank_mask:0xf bound_ctrl:1
	v_add_f32_dpp v113, v113, v113 row_half_mirror row_mask:0xf bank_mask:0xf bound_ctrl:1
	v_pk_fma_f32 v[110:111], v[80:81], v[32:33], v[110:111] op_sel:[0,1,0]
	v_add_f32_dpp v112, v112, v112 row_mirror row_mask:0xf bank_mask:0xf bound_ctrl:1
	v_add_f32_dpp v113, v113, v113 row_mirror row_mask:0xf bank_mask:0xf bound_ctrl:1
	v_pk_fma_f32 v[74:75], v[112:113], v[38:39], v[104:105] op_sel_hi:[1,0,1] neg_lo:[1,0,0] neg_hi:[1,0,0]
	v_pk_fma_f32 v[76:77], v[112:113], v[38:39], v[106:107] op_sel:[0,1,0] neg_lo:[1,0,0] neg_hi:[1,0,0]
	v_pk_mul_f32 v[114:115], v[74:75], v[26:27] op_sel_hi:[1,0]
	v_pk_fma_f32 v[78:79], v[112:113], v[40:41], v[108:109] op_sel_hi:[1,0,1] neg_lo:[1,0,0] neg_hi:[1,0,0]
	v_pk_fma_f32 v[114:115], v[76:77], v[26:27], v[114:115] op_sel:[0,1,0]
	v_pk_fma_f32 v[80:81], v[112:113], v[40:41], v[110:111] op_sel:[0,1,0] neg_lo:[1,0,0] neg_hi:[1,0,0]
	v_pk_fma_f32 v[114:115], v[78:79], v[28:29], v[114:115] op_sel_hi:[1,0,1]
	v_pk_fma_f32 v[114:115], v[80:81], v[28:29], v[114:115] op_sel:[0,1,0]
	ds_write_b64 v96, v[114:115] offset:4352
	s_waitcnt lgkmcnt(1)
	ds_read_b128 v[26:29], v0 offset:768
	ds_read_b128 v[30:33], v0 offset:4864
	ds_read_b128 v[34:37], v0 offset:8960
	ds_read_b128 v[42:45], v0 offset:17152
	ds_read_b128 v[38:41], v0 offset:21248
	ds_read_b64 v[82:83], v95 offset:768
	v_pk_mul_f32 v[112:113], v[74:75], v[62:63] op_sel_hi:[1,0]
	v_pk_mul_f32 v[104:105], v[84:85], v[54:55] op_sel_hi:[1,0]
	v_pk_fma_f32 v[112:113], v[76:77], v[62:63], v[112:113] op_sel:[0,1,0]
	v_pk_mul_f32 v[106:107], v[84:85], v[54:55] op_sel:[0,1]
	v_pk_fma_f32 v[112:113], v[78:79], v[64:65], v[112:113] op_sel_hi:[1,0,1]
	v_pk_mul_f32 v[108:109], v[84:85], v[56:57] op_sel_hi:[1,0]
	v_pk_fma_f32 v[112:113], v[80:81], v[64:65], v[112:113] op_sel:[0,1,0]
	v_pk_mul_f32 v[110:111], v[84:85], v[56:57] op_sel:[0,1]
	v_pk_fma_f32 v[104:105], v[74:75], v[50:51], v[104:105] op_sel_hi:[1,0,1]
	v_add_f32_dpp v112, v112, v112 quad_perm:[1,0,3,2] row_mask:0xf bank_mask:0xf bound_ctrl:1
	v_add_f32_dpp v113, v113, v113 quad_perm:[1,0,3,2] row_mask:0xf bank_mask:0xf bound_ctrl:1
	v_pk_fma_f32 v[106:107], v[76:77], v[50:51], v[106:107] op_sel:[0,1,0]
	v_add_f32_dpp v112, v112, v112 quad_perm:[2,3,0,1] row_mask:0xf bank_mask:0xf bound_ctrl:1
	v_add_f32_dpp v113, v113, v113 quad_perm:[2,3,0,1] row_mask:0xf bank_mask:0xf bound_ctrl:1
	v_pk_fma_f32 v[108:109], v[78:79], v[52:53], v[108:109] op_sel_hi:[1,0,1]
	v_add_f32_dpp v112, v112, v112 row_half_mirror row_mask:0xf bank_mask:0xf bound_ctrl:1
	v_add_f32_dpp v113, v113, v113 row_half_mirror row_mask:0xf bank_mask:0xf bound_ctrl:1
	v_pk_fma_f32 v[110:111], v[80:81], v[52:53], v[110:111] op_sel:[0,1,0]
	v_add_f32_dpp v112, v112, v112 row_mirror row_mask:0xf bank_mask:0xf bound_ctrl:1
	v_add_f32_dpp v113, v113, v113 row_mirror row_mask:0xf bank_mask:0xf bound_ctrl:1
	v_pk_fma_f32 v[74:75], v[112:113], v[58:59], v[104:105] op_sel_hi:[1,0,1] neg_lo:[1,0,0] neg_hi:[1,0,0]
	v_pk_fma_f32 v[76:77], v[112:113], v[58:59], v[106:107] op_sel:[0,1,0] neg_lo:[1,0,0] neg_hi:[1,0,0]
	v_pk_mul_f32 v[114:115], v[74:75], v[46:47] op_sel_hi:[1,0]
	v_pk_fma_f32 v[78:79], v[112:113], v[60:61], v[108:109] op_sel_hi:[1,0,1] neg_lo:[1,0,0] neg_hi:[1,0,0]
	v_pk_fma_f32 v[114:115], v[76:77], v[46:47], v[114:115] op_sel:[0,1,0]
	v_pk_fma_f32 v[80:81], v[112:113], v[60:61], v[110:111] op_sel:[0,1,0] neg_lo:[1,0,0] neg_hi:[1,0,0]
	v_pk_fma_f32 v[114:115], v[78:79], v[48:49], v[114:115] op_sel_hi:[1,0,1]
	v_pk_fma_f32 v[114:115], v[80:81], v[48:49], v[114:115] op_sel:[0,1,0]
	ds_write_b64 v96, v[114:115] offset:6528
	s_addk_i32 s15, 0x100
	v_add_u32_e32 v0, 0x400, v0
	s_cmpk_eq_i32 s15, 0x500
	v_add_u32_e32 v95, 0x400, v95
	v_add_u32_e32 v96, 0x2200, v96
	s_cbranch_scc0 .LBB0_252
	s_setprio 0

.Lsc_w1:
	s_add_i32 s17, s12, 1
	v_lshl_or_b32 v0, s17, 4, v87
	s_waitcnt lgkmcnt(0)
	s_bitcmp1_b32 s17, 0
	s_cselect_b32 s14, 0x6000, 0
	v_lshlrev_b32_e32 v48, 16, v127
	v_lshlrev_b32_e32 v42, 16, v128
	v_and_b32_e32 v43, 0xffff0000, v128
	v_lshlrev_b32_e32 v44, 16, v130
	v_and_b32_e32 v45, 0xffff0000, v130
	v_lshlrev_b32_e32 v56, 16, v122
	v_and_b32_e32 v57, 0xffff0000, v122
	v_lshlrev_b32_e32 v58, 16, v123
	v_and_b32_e32 v59, 0xffff0000, v123
	v_lshlrev_b32_e32 v28, 16, v126
	v_and_b32_e32 v29, 0xffff0000, v126
	v_lshlrev_b32_e32 v46, 16, v132
	v_and_b32_e32 v47, 0xffff0000, v132
	v_and_b32_e32 v49, 0xffff0000, v127
	v_lshlrev_b32_e32 v32, 16, v129
	v_and_b32_e32 v33, 0xffff0000, v129
	v_lshlrev_b32_e32 v34, 16, v131
	v_and_b32_e32 v35, 0xffff0000, v131
	v_lshlrev_b32_e32 v36, 16, v133
	v_and_b32_e32 v37, 0xffff0000, v133
	v_lshlrev_b32_e32 v38, 16, v134
	v_and_b32_e32 v39, 0xffff0000, v134
	v_lshlrev_b32_e32 v50, 16, v124
	v_and_b32_e32 v51, 0xffff0000, v124
	v_lshlrev_b32_e32 v52, 16, v120
	v_and_b32_e32 v53, 0xffff0000, v120
	v_lshlrev_b32_e32 v40, 16, v135
	v_and_b32_e32 v41, 0xffff0000, v135
	v_lshlrev_b32_e32 v30, 16, v125
	v_and_b32_e32 v31, 0xffff0000, v125
	v_lshlrev_b32_e32 v54, 16, v121
	v_and_b32_e32 v55, 0xffff0000, v121
	s_cmpk_ge_i32 s12, 0xfe
	s_cbranch_scc1 .Lsc_nopf
	s_add_i32 s17, s12, 2
	v_lshl_or_b32 v140, s17, 4, v87
	v_mad_u64_u32 v[136:137], vcc, v140, s37, v[72:73]
	v_mad_u64_u32 v[138:139], vcc, v140, s11, v[70:71]
	global_load_dwordx2 v[122:123], v[136:137], off
	global_load_dwordx2 v[126:127], v[138:139], off
	global_load_dwordx2 v[128:129], v[138:139], off offset:-3584
	global_load_dwordx2 v[120:121], v[136:137], off offset:1024
	global_load_dwordx2 v[130:131], v[138:139], off offset:2048
	global_load_dwordx2 v[132:133], v[138:139], off offset:-1536
	global_load_dwordx2 v[134:135], v[138:139], off offset:1024
	global_load_dwordx2 v[124:125], v[138:139], off offset:-2560
.Lsc_nopf:
	v_pk_add_f32 v[26:27], v[42:43], v[28:29] neg_lo:[0,1] neg_hi:[0,1]
	v_pk_add_f32 v[42:43], v[46:47], v[44:45] neg_lo:[0,1] neg_hi:[0,1]
	v_mul_f32_e32 v62, 0xbfb8aa3b, v56
	v_mul_f32_e32 v63, 0xbfb8aa3b, v57
	v_pk_add_f32 v[50:51], v[50:51], v[38:39] neg_lo:[0,1] neg_hi:[0,1]
	v_pk_add_f32 v[56:57], v[52:53], -1.0 op_sel_hi:[1,0]
	v_pk_add_f32 v[46:47], v[32:33], v[48:49] neg_lo:[0,1] neg_hi:[0,1]
	v_mul_f32_e32 v64, 0xbfb8aa3b, v58
	v_mul_f32_e32 v65, 0xbfb8aa3b, v59
	v_pk_add_f32 v[58:59], v[30:31], v[40:41] neg_lo:[0,1] neg_hi:[0,1]
	v_pk_add_f32 v[60:61], v[54:55], -1.0 op_sel_hi:[1,0]
	v_pk_fma_f32 v[28:29], v[10:11], v[26:27], v[28:29]
	v_pk_fma_f32 v[32:33], v[2:3], v[42:43], v[44:45]
	v_pk_fma_f32 v[26:27], v[6:7], v[50:51], v[38:39]
	v_pk_fma_f32 v[42:43], v[18:19], v[56:57], 1.0 op_sel_hi:[1,1,0]
	v_pk_fma_f32 v[30:31], v[12:13], v[46:47], v[48:49]
	v_pk_fma_f32 v[44:45], v[8:9], v[58:59], v[40:41]
	v_pk_fma_f32 v[46:47], v[20:21], v[60:61], 1.0 op_sel_hi:[1,1,0]
	v_pk_mul_f32 v[48:49], v[14:15], v[26:27]
	v_pk_mul_f32 v[40:41], v[26:27], v[42:43]
	v_pk_mul_f32 v[50:51], v[16:17], v[44:45]
	v_pk_mul_f32 v[42:43], v[44:45], v[46:47]
	v_pk_mul_f32 v[26:27], v[48:49], v[48:49]
	v_pk_mul_f32 v[44:45], v[28:29], v[40:41]
	v_pk_mul_f32 v[46:47], v[50:51], v[50:51]
	v_pk_mul_f32 v[44:45], v[22:23], v[44:45]
	v_add_f32_e32 v58, v26, v27
	v_add_f32_e32 v44, 0, v44
	v_add_f32_e32 v46, v46, v58
	v_pk_mul_f32 v[56:57], v[30:31], v[42:43]
	v_add_f32_e32 v44, v45, v44
	v_add_f32_e32 v45, v47, v46
	v_pk_mul_f32 v[26:27], v[24:25], v[56:57]
	v_pk_add_f32 v[36:37], v[36:37], v[34:35] neg_lo:[0,1] neg_hi:[0,1]
	v_add_f32_dpp v45, v45, v45 quad_perm:[1,0,3,2] row_mask:0xf bank_mask:0xf bound_ctrl:1
	v_add_f32_e32 v26, v26, v44
	v_add_f32_e32 v26, v27, v26
	v_add_f32_dpp v44, v45, v45 quad_perm:[2,3,0,1] row_mask:0xf bank_mask:0xf bound_ctrl:1
	v_pk_fma_f32 v[34:35], v[4:5], v[36:37], v[34:35]
	v_add_f32_dpp v26, v26, v26 quad_perm:[1,0,3,2] row_mask:0xf bank_mask:0xf bound_ctrl:1
	v_add_f32_dpp v27, v44, v44 row_half_mirror row_mask:0xf bank_mask:0xf bound_ctrl:1
	v_exp_f32_e32 v36, v62
	v_exp_f32_e32 v37, v63
	v_add_f32_dpp v27, v27, v27 row_mirror row_mask:0xf bank_mask:0xf bound_ctrl:1
	v_rsq_f32_e32 v27, v27
	v_exp_f32_e32 v38, v64
	v_exp_f32_e32 v39, v65
	v_add_f32_dpp v26, v26, v26 quad_perm:[2,3,0,1] row_mask:0xf bank_mask:0xf bound_ctrl:1
	v_min_f32_e32 v46, 0x5368d4a5, v27
	v_pk_mul_f32 v[44:45], v[48:49], v[46:47] op_sel_hi:[1,0]
	v_add_f32_dpp v26, v26, v26 row_half_mirror row_mask:0xf bank_mask:0xf bound_ctrl:1
	v_pk_mul_f32 v[46:47], v[50:51], v[46:47] op_sel_hi:[1,0]
	v_pk_mul_f32 v[48:49], v[44:45], v[52:53]
	v_mov_b32_dpp v27, v26 row_mirror row_mask:0xf bank_mask:0xf bound_ctrl:1
	v_add_u32_e32 v52, s14, v91
	v_pk_mul_f32 v[50:51], v[46:47], v[54:55]
	ds_write_b128 v52, v[28:31]
	ds_write_b128 v52, v[36:39] offset:4096
	ds_write_b128 v52, v[40:43] offset:8192
	ds_write_b128 v52, v[32:35] offset:12288
	ds_write_b128 v52, v[44:47] offset:16384
	ds_write_b128 v52, v[48:51] offset:20480
	s_and_saveexec_b64 s[24:25], s[2:3]
	s_cbranch_execz .Lsc_norkb
	v_lshlrev_b64 v[28:29], 5, v[0:1]
	v_lshl_add_u64 v[28:29], s[0:1], 0, v[28:29]
	v_add_f32_e32 v0, v26, v27
	global_store_dword v[28:29], v0, off
